# non-temporal policy on the RN row loads and residual-stream stores (6 in-place RN phases)
# baseline (speedup 1.0000x reference)
.LBB0_680:
	v_lshlrev_b32_e32 v127, 16, v13
	v_lshlrev_b32_e32 v126, 16, v12
	v_and_b32_e32 v13, 0xffff0000, v13
	v_and_b32_e32 v12, 0xffff0000, v12
	v_lshlrev_b32_e32 v131, 16, v15
	v_lshlrev_b32_e32 v130, 16, v14
	v_and_b32_e32 v15, 0xffff0000, v15
	v_and_b32_e32 v14, 0xffff0000, v14
	v_lshlrev_b32_e32 v122, 16, v8
	v_and_b32_e32 v123, 0xffff0000, v8
	v_lshlrev_b32_e32 v124, 16, v10
	v_pk_mul_f32 v[128:129], v[12:13], v[12:13]
	v_pk_mul_f32 v[132:133], v[14:15], v[14:15]
	v_lshlrev_b32_e32 v8, 16, v9
	v_pk_fma_f32 v[128:129], v[126:127], v[126:127], v[128:129]
	v_pk_fma_f32 v[132:133], v[130:131], v[130:131], v[132:133]
	v_mul_f32_e32 v125, v122, v122
	v_mul_f32_e32 v135, v123, v123
	v_and_b32_e32 v9, 0xffff0000, v9
	v_mul_f32_e32 v98, v8, v8
	v_mov_b32_e32 v134, v124
	v_and_b32_e32 v121, 0xffff0000, v10
	v_lshlrev_b32_e32 v10, 16, v11
	v_and_b32_e32 v11, 0xffff0000, v11
	v_pk_add_f32 v[128:129], v[128:129], v[128:129] op_sel_hi:[0,1]
	v_pk_add_f32 v[132:133], v[132:133], v[132:133] op_sel_hi:[0,1]
	v_pk_fma_f32 v[136:137], v[8:9], v[8:9], v[98:99] op_sel_hi:[1,1,0]
	v_pk_add_f32 v[134:135], v[124:125], v[134:135]
	v_mul_f32_e32 v136, v121, v121
	v_mul_f32_e32 v128, v10, v10
	v_mul_f32_e32 v132, v11, v11
	v_mul_f32_e32 v138, v124, v124
	v_mov_b32_e32 v139, v135
	v_pk_add_f32 v[134:135], v[138:139], v[136:137]
	v_pk_add_f32 v[128:129], v[128:129], v[132:133]
	v_lshlrev_b32_e32 v136, 16, v2
	v_pk_add_f32 v[128:129], v[134:135], v[128:129]
	v_lshlrev_b32_e32 v134, 16, v0
	v_add_f32_e32 v98, v128, v129
	ds_bpermute_b32 v125, v109, v98
	v_and_b32_e32 v135, 0xffff0000, v0
	v_lshlrev_b32_e32 v128, 16, v4
	v_and_b32_e32 v129, 0xffff0000, v4
	v_lshlrev_b32_e32 v4, 16, v5
	s_waitcnt lgkmcnt(0)
	v_add_f32_e32 v98, v98, v125
	ds_bpermute_b32 v125, v114, v98
	v_and_b32_e32 v5, 0xffff0000, v5
	v_lshlrev_b32_e32 v132, 16, v6
	v_and_b32_e32 v133, 0xffff0000, v6
	v_lshlrev_b32_e32 v6, 16, v7
	s_waitcnt lgkmcnt(0)
	v_add_f32_e32 v98, v98, v125
	ds_bpermute_b32 v125, v115, v98
	v_and_b32_e32 v7, 0xffff0000, v7
	s_ashr_i32 s23, s22, 31
	s_lshl_b64 s[22:23], s[22:23], 11
	s_waitcnt lgkmcnt(0)
	v_add_f32_e32 v98, v98, v125
	ds_bpermute_b32 v125, v116, v98
	s_waitcnt lgkmcnt(0)
	v_add_f32_e32 v98, v98, v125
	ds_bpermute_b32 v125, v117, v98
	s_waitcnt lgkmcnt(0)
	v_add_f32_e32 v98, v98, v125
	ds_bpermute_b32 v125, v118, v98
	s_waitcnt lgkmcnt(0)
	v_add_f32_e32 v0, v98, v125
	v_fmamk_f32 v0, v0, 0x3a800000, v119
	v_mul_f32_e32 v98, 0x4f800000, v0
	v_cmp_gt_f32_e32 vcc, s36, v0
	s_nop 1
	v_cndmask_b32_e32 v98, v0, v98, vcc
	v_sqrt_f32_e32 v125, v98
	v_lshlrev_b32_e32 v0, 16, v1
	v_and_b32_e32 v1, 0xffff0000, v1
	v_add_u32_e32 v137, -1, v125
	v_fma_f32 v138, -v137, v125, v98
	v_cmp_ge_f32_e64 s[2:3], 0, v138
	v_add_u32_e32 v138, 1, v125
	s_nop 0
	v_cndmask_b32_e64 v137, v125, v137, s[2:3]
	v_fma_f32 v125, -v138, v125, v98
	v_cmp_lt_f32_e64 s[2:3], 0, v125
	s_nop 1
	v_cndmask_b32_e64 v125, v137, v138, s[2:3]
	v_mul_f32_e32 v137, 0x37800000, v125
	v_cndmask_b32_e32 v125, v125, v137, vcc
	v_cmp_class_f32_e32 vcc, v98, v120
	v_and_b32_e32 v137, 0xffff0000, v2
	v_lshlrev_b32_e32 v2, 16, v3
	v_cndmask_b32_e32 v98, v125, v98, vcc
	v_div_scale_f32 v125, s[2:3], v98, v98, 1.0
	v_rcp_f32_e32 v138, v125
	v_and_b32_e32 v3, 0xffff0000, v3
	v_fma_f32 v139, -v125, v138, 1.0
	v_fmac_f32_e32 v138, v139, v138
	v_div_scale_f32 v139, vcc, 1.0, v98, 1.0
	v_mul_f32_e32 v140, v139, v138
	v_fma_f32 v141, -v125, v140, v139
	v_fmac_f32_e32 v140, v141, v138
	v_fma_f32 v125, -v125, v140, v139
	v_div_fmas_f32 v125, v125, v138, v140
	v_div_fixup_f32 v98, v125, v98, 1.0
	v_mov_b32_e32 v138, v126
	v_mov_b32_e32 v139, v12
	v_mov_b32_e32 v12, v127
	v_pk_mul_f32 v[138:139], v[98:99], v[138:139] op_sel_hi:[0,1]
	v_pk_mul_f32 v[12:13], v[98:99], v[12:13] op_sel_hi:[0,1]
	v_pk_mul_f32 v[8:9], v[98:99], v[8:9] op_sel_hi:[0,1]
	v_mov_b32_e32 v125, v121
	v_pk_fma_f32 v[4:5], v[62:63], v[12:13], v[4:5]
	v_pk_fma_f32 v[12:13], v[60:61], v[138:139], v[128:129]
	v_mov_b32_e32 v126, v130
	v_mov_b32_e32 v127, v14
	v_mov_b32_e32 v14, v131
	v_pk_fma_f32 v[8:9], v[34:35], v[8:9], v[0:1]
	v_pk_mul_f32 v[0:1], v[98:99], v[124:125] op_sel_hi:[0,1]
	v_pk_mul_f32 v[10:11], v[98:99], v[10:11] op_sel_hi:[0,1]
	v_pk_mul_f32 v[126:127], v[98:99], v[126:127] op_sel_hi:[0,1]
	v_pk_mul_f32 v[14:15], v[98:99], v[14:15] op_sel_hi:[0,1]
	v_pk_fma_f32 v[10:11], v[58:59], v[10:11], v[2:3]
	v_pk_fma_f32 v[124:125], v[56:57], v[0:1], v[136:137]
	v_pk_mul_f32 v[0:1], v[4:5], v[4:5]
	v_pk_mul_f32 v[2:3], v[12:13], v[12:13]
	v_pk_fma_f32 v[6:7], v[22:23], v[14:15], v[6:7]
	v_pk_fma_f32 v[14:15], v[20:21], v[126:127], v[132:133]
	v_pk_mov_b32 v[126:127], v[2:3], v[0:1] op_sel:[1,0]
	v_mov_b32_e32 v3, v1
	v_pk_mul_f32 v[122:123], v[98:99], v[122:123] op_sel_hi:[0,1]
	v_pk_add_f32 v[0:1], v[126:127], v[2:3]
	v_pk_fma_f32 v[122:123], v[32:33], v[122:123], v[134:135]
	v_pk_add_f32 v[0:1], v[0:1], v[0:1] op_sel_hi:[0,1]
	v_pk_mul_f32 v[2:3], v[6:7], v[6:7]
	v_pk_mul_f32 v[126:127], v[14:15], v[14:15]
	v_mul_f32_e32 v0, v122, v122
	v_pk_mov_b32 v[128:129], v[126:127], v[2:3] op_sel:[1,0]
	v_mov_b32_e32 v127, v3
	v_pk_add_f32 v[2:3], v[128:129], v[126:127]
	v_pk_fma_f32 v[126:127], v[122:123], v[122:123], v[0:1] op_sel_hi:[1,1,0]
	v_mul_f32_e32 v0, v8, v8
	v_pk_add_f32 v[2:3], v[2:3], v[2:3] op_sel_hi:[0,1]
	v_pk_fma_f32 v[128:129], v[8:9], v[8:9], v[0:1] op_sel_hi:[1,1,0]
	v_mul_f32_e32 v126, v124, v124
	v_mul_f32_e32 v128, v125, v125
	v_mul_f32_e32 v0, v10, v10
	v_mul_f32_e32 v2, v11, v11
	v_pk_add_f32 v[126:127], v[126:127], v[128:129]
	v_pk_add_f32 v[0:1], v[0:1], v[2:3]
	v_cvt_pk_bf16_f32 v2, v14, v15
	v_pk_add_f32 v[0:1], v[126:127], v[0:1]
	v_lshl_add_u64 v[126:127], v[100:101], 0, s[22:23]
	v_add_f32_e32 v0, v0, v1
	ds_bpermute_b32 v1, v109, v0
	v_cvt_pk_bf16_f32 v3, v6, v7
	s_waitcnt lgkmcnt(0)
	v_add_f32_e32 v0, v0, v1
	ds_bpermute_b32 v1, v114, v0
	s_waitcnt lgkmcnt(0)
	v_add_f32_e32 v0, v0, v1
	ds_bpermute_b32 v1, v115, v0
	s_waitcnt lgkmcnt(0)
	v_add_f32_e32 v0, v0, v1
	ds_bpermute_b32 v1, v116, v0
	s_waitcnt lgkmcnt(0)
	v_add_f32_e32 v0, v0, v1
	ds_bpermute_b32 v1, v117, v0
	s_waitcnt lgkmcnt(0)
	v_add_f32_e32 v98, v0, v1
	ds_bpermute_b32 v121, v118, v98
	v_cvt_pk_bf16_f32 v0, v12, v13
	v_cvt_pk_bf16_f32 v1, v4, v5
	global_store_dwordx4 v[126:127], v[0:3], off nt
	s_waitcnt lgkmcnt(0)
	v_add_f32_e32 v98, v98, v121
	v_fmamk_f32 v98, v98, 0x3a800000, v119
	v_mul_f32_e32 v121, 0x4f800000, v98
	v_cmp_gt_f32_e32 vcc, s36, v98
	v_cvt_pk_bf16_f32 v0, v122, v123
	v_cvt_pk_bf16_f32 v1, v8, v9
	v_cndmask_b32_e32 v98, v98, v121, vcc
	v_sqrt_f32_e32 v121, v98
	s_nop 0
	v_add_u32_e32 v2, -1, v121
	v_fma_f32 v3, -v2, v121, v98
	v_cmp_ge_f32_e64 s[2:3], 0, v3
	v_add_u32_e32 v3, 1, v121
	s_nop 0
	v_cndmask_b32_e64 v2, v121, v2, s[2:3]
	v_fma_f32 v121, -v3, v121, v98
	v_cmp_lt_f32_e64 s[2:3], 0, v121
	s_nop 1
	v_cndmask_b32_e64 v2, v2, v3, s[2:3]
	v_mul_f32_e32 v3, 0x37800000, v2
	v_cndmask_b32_e32 v2, v2, v3, vcc
	v_cmp_class_f32_e32 vcc, v98, v120
	v_cvt_pk_bf16_f32 v3, v10, v11
	s_nop 0
	v_cndmask_b32_e32 v98, v2, v98, vcc
	v_div_scale_f32 v121, s[2:3], v98, v98, 1.0
	v_rcp_f32_e32 v128, v121
	v_cvt_pk_bf16_f32 v2, v124, v125
	global_store_dwordx4 v[126:127], v[0:3], off offset:1024 nt
	v_lshl_add_u64 v[126:127], v[102:103], 0, s[22:23]
	s_nop 0
	v_fma_f32 v0, -v121, v128, 1.0
	v_fmac_f32_e32 v128, v0, v128
	v_div_scale_f32 v0, vcc, 1.0, v98, 1.0
	v_mul_f32_e32 v1, v0, v128
	v_fma_f32 v2, -v121, v1, v0
	v_fmac_f32_e32 v1, v2, v128
	v_fma_f32 v0, -v121, v1, v0
	v_div_fmas_f32 v0, v0, v128, v1
	v_div_fixup_f32 v98, v0, v98, 1.0
	v_pk_mul_f32 v[0:1], v[12:13], v[98:99] op_sel_hi:[1,0]
	v_pk_mul_f32 v[2:3], v[4:5], v[98:99] op_sel_hi:[1,0]
	v_pk_mul_f32 v[4:5], v[14:15], v[98:99] op_sel_hi:[1,0]
	v_pk_mul_f32 v[6:7], v[6:7], v[98:99] op_sel_hi:[1,0]
	s_waitcnt vmcnt(2)
	v_pk_fma_f32 v[2:3], v[78:79], v[2:3], v[38:39]
	v_pk_fma_f32 v[0:1], v[76:77], v[0:1], v[36:37]
	v_pk_fma_f32 v[6:7], v[66:67], v[6:7], v[26:27]
	v_pk_fma_f32 v[4:5], v[64:65], v[4:5], v[24:25]
	v_cvt_pk_bf16_f32 v0, v0, v1
	v_cvt_pk_bf16_f32 v1, v2, v3
	v_cvt_pk_bf16_f32 v2, v4, v5
	v_cvt_pk_bf16_f32 v3, v6, v7
	global_store_dwordx4 v[126:127], v[0:3], off
	v_pk_mul_f32 v[4:5], v[124:125], v[98:99] op_sel_hi:[1,0]
	v_pk_mul_f32 v[6:7], v[10:11], v[98:99] op_sel_hi:[1,0]
	v_pk_mul_f32 v[0:1], v[122:123], v[98:99] op_sel_hi:[1,0]
	v_pk_mul_f32 v[2:3], v[8:9], v[98:99] op_sel_hi:[1,0]
	v_pk_fma_f32 v[0:1], v[68:69], v[0:1], v[28:29]
	v_pk_fma_f32 v[2:3], v[70:71], v[2:3], v[30:31]
	v_pk_fma_f32 v[6:7], v[74:75], v[6:7], v[18:19]
	v_pk_fma_f32 v[4:5], v[72:73], v[4:5], v[16:17]
	v_cvt_pk_bf16_f32 v0, v0, v1
	v_cvt_pk_bf16_f32 v1, v2, v3
	v_cvt_pk_bf16_f32 v2, v4, v5
	v_cvt_pk_bf16_f32 v3, v6, v7
	global_store_dwordx4 v[126:127], v[0:3], off offset:1024
	v_mov_b64_e32 v[4:5], v[84:85]
	v_mov_b64_e32 v[8:9], v[88:89]
	v_mov_b64_e32 v[0:1], v[92:93]
	v_mov_b64_e32 v[12:13], v[80:81]
	v_mov_b64_e32 v[2:3], v[94:95]
	v_mov_b64_e32 v[6:7], v[86:87]
	v_mov_b64_e32 v[10:11], v[90:91]
	v_mov_b64_e32 v[14:15], v[82:83]

.LBB0_682:
	s_add_i32 s2, s6, -3
	s_ashr_i32 s2, s2, 13
	s_cmp_eq_u32 s2, s40
	s_cbranch_scc1 .LBB0_684
	s_mul_i32 s7, s2, 0x6000
	s_mul_hi_i32 s3, s2, 0x6000
	s_add_u32 s22, s46, s7
	s_addc_u32 s23, s47, s3
	v_lshlrev_b32_e32 v98, 4, v108
	v_lshl_add_u64 v[16:17], s[22:23], 0, v[98:99]
	v_add_co_u32_e32 v26, vcc, s24, v16
	v_lshl_add_u64 v[18:19], v[16:17], 0, s[16:17]
	s_nop 0
	v_addc_co_u32_e32 v27, vcc, 0, v17, vcc
	v_lshl_add_u64 v[24:25], v[16:17], 0, s[18:19]
	global_load_dwordx4 v[20:23], v[110:111], off offset:16
	global_load_dwordx4 v[40:43], v[110:111], off
	global_load_dwordx4 v[44:47], v[26:27], off
	global_load_dwordx4 v[32:35], v[18:19], off offset:16
	global_load_dwordx4 v[48:51], v[24:25], off offset:16
	global_load_dwordx4 v[52:55], v[110:111], off offset:2064
	global_load_dwordx4 v[56:59], v[110:111], off offset:2048
	global_load_dwordx4 v[60:63], v[18:19], off offset:2048
	global_load_dwordx4 v[64:67], v[24:25], off offset:2064
	global_load_dwordx4 v[68:71], v[24:25], off offset:2048
	global_load_dwordx4 v[72:75], v[112:113], off offset:16
	global_load_dwordx4 v[76:79], v[112:113], off
	global_load_dwordx4 v[122:125], v[18:19], off offset:2064
	v_add_co_u32_e32 v18, vcc, s25, v16
	v_lshl_add_u64 v[28:29], v[16:17], 0, s[20:21]
	s_nop 0
	v_addc_co_u32_e32 v19, vcc, 0, v17, vcc
	v_add_co_u32_e32 v36, vcc, s27, v16
	global_load_dwordx4 v[126:129], v[18:19], off
	global_load_dwordx4 v[130:133], v[112:113], off offset:2064
	global_load_dwordx4 v[134:137], v[112:113], off offset:2048
	v_addc_co_u32_e32 v37, vcc, 0, v17, vcc
	global_load_dwordx4 v[16:19], v[28:29], off offset:2064 nt
	global_load_dwordx4 v[24:27], v[28:29], off offset:16 nt
	s_nop 0
	global_load_dwordx4 v[28:31], v[28:29], off offset:2048 nt
	s_nop 0
	global_load_dwordx4 v[36:39], v[36:37], off nt
	s_mov_b32 s40, s2
	s_waitcnt vmcnt(15)
	v_pk_add_f32 v[50:51], v[50:51], 1.0 op_sel_hi:[1,0]
	v_pk_add_f32 v[48:49], v[48:49], 1.0 op_sel_hi:[1,0]
	s_waitcnt vmcnt(10)
	v_pk_add_f32 v[70:71], v[70:71], 1.0 op_sel_hi:[1,0]
	v_pk_mul_f32 v[22:23], v[22:23], v[34:35]
	v_pk_mul_f32 v[20:21], v[20:21], v[32:33]
	v_pk_mul_f32 v[34:35], v[58:59], v[62:63]
	v_pk_mul_f32 v[32:33], v[56:57], v[60:61]
	v_pk_add_f32 v[68:69], v[68:69], 1.0 op_sel_hi:[1,0]
	s_waitcnt vmcnt(7)
	v_pk_mul_f32 v[58:59], v[54:55], v[124:125]
	v_pk_mul_f32 v[56:57], v[52:53], v[122:123]
	v_pk_add_f32 v[52:53], v[66:67], 1.0 op_sel_hi:[1,0]
	v_pk_add_f32 v[54:55], v[64:65], 1.0 op_sel_hi:[1,0]
	v_pk_mul_f32 v[62:63], v[42:43], v[46:47]
	v_pk_mul_f32 v[60:61], v[40:41], v[44:45]
	s_waitcnt vmcnt(6)
	v_pk_add_f32 v[40:41], v[128:129], 1.0 op_sel_hi:[1,0]
	v_pk_add_f32 v[42:43], v[126:127], 1.0 op_sel_hi:[1,0]
	v_pk_mul_f32 v[66:67], v[74:75], v[50:51]
	v_pk_mul_f32 v[64:65], v[72:73], v[48:49]
	s_waitcnt vmcnt(4)
	v_pk_mul_f32 v[70:71], v[136:137], v[70:71]
	v_pk_mul_f32 v[68:69], v[134:135], v[68:69]
	v_pk_mul_f32 v[74:75], v[132:133], v[52:53]
	v_pk_mul_f32 v[72:73], v[130:131], v[54:55]
	v_pk_mul_f32 v[78:79], v[78:79], v[40:41]
	v_pk_mul_f32 v[76:77], v[76:77], v[42:43]

.LBB0_686:
	v_lshlrev_b32_e32 v127, 16, v93
	v_lshlrev_b32_e32 v126, 16, v92
	v_and_b32_e32 v93, 0xffff0000, v93
	v_and_b32_e32 v92, 0xffff0000, v92
	v_lshlrev_b32_e32 v131, 16, v95
	v_lshlrev_b32_e32 v130, 16, v94
	v_and_b32_e32 v95, 0xffff0000, v95
	v_and_b32_e32 v94, 0xffff0000, v94
	v_lshlrev_b32_e32 v122, 16, v88
	v_and_b32_e32 v123, 0xffff0000, v88
	v_lshlrev_b32_e32 v124, 16, v90
	v_pk_mul_f32 v[128:129], v[92:93], v[92:93]
	v_pk_mul_f32 v[132:133], v[94:95], v[94:95]
	v_lshlrev_b32_e32 v88, 16, v89
	v_pk_fma_f32 v[128:129], v[126:127], v[126:127], v[128:129]
	v_pk_fma_f32 v[132:133], v[130:131], v[130:131], v[132:133]
	v_mul_f32_e32 v125, v122, v122
	v_mul_f32_e32 v135, v123, v123
	v_and_b32_e32 v89, 0xffff0000, v89
	v_mul_f32_e32 v98, v88, v88
	v_mov_b32_e32 v134, v124
	v_and_b32_e32 v121, 0xffff0000, v90
	v_lshlrev_b32_e32 v90, 16, v91
	v_and_b32_e32 v91, 0xffff0000, v91
	v_pk_add_f32 v[128:129], v[128:129], v[128:129] op_sel_hi:[0,1]
	v_pk_add_f32 v[132:133], v[132:133], v[132:133] op_sel_hi:[0,1]
	v_pk_fma_f32 v[136:137], v[88:89], v[88:89], v[98:99] op_sel_hi:[1,1,0]
	v_pk_add_f32 v[134:135], v[124:125], v[134:135]
	v_mul_f32_e32 v136, v121, v121
	v_mul_f32_e32 v128, v90, v90
	v_mul_f32_e32 v132, v91, v91
	v_mul_f32_e32 v138, v124, v124
	v_mov_b32_e32 v139, v135
	v_pk_add_f32 v[134:135], v[138:139], v[136:137]
	v_pk_add_f32 v[128:129], v[128:129], v[132:133]
	v_lshlrev_b32_e32 v136, 16, v82
	v_pk_add_f32 v[128:129], v[134:135], v[128:129]
	v_lshlrev_b32_e32 v134, 16, v80
	v_add_f32_e32 v98, v128, v129
	ds_bpermute_b32 v125, v109, v98
	v_and_b32_e32 v135, 0xffff0000, v80
	v_lshlrev_b32_e32 v128, 16, v84
	v_and_b32_e32 v129, 0xffff0000, v84
	v_lshlrev_b32_e32 v84, 16, v85
	s_waitcnt lgkmcnt(0)
	v_add_f32_e32 v98, v98, v125
	ds_bpermute_b32 v125, v114, v98
	v_and_b32_e32 v85, 0xffff0000, v85
	v_lshlrev_b32_e32 v132, 16, v86
	v_and_b32_e32 v133, 0xffff0000, v86
	v_lshlrev_b32_e32 v86, 16, v87
	s_waitcnt lgkmcnt(0)
	v_add_f32_e32 v98, v98, v125
	ds_bpermute_b32 v125, v115, v98
	v_and_b32_e32 v87, 0xffff0000, v87
	s_add_i32 s22, s6, -2
	s_cmp_ge_i32 s22, s26
	s_waitcnt lgkmcnt(0)
	v_add_f32_e32 v98, v98, v125
	ds_bpermute_b32 v125, v116, v98
	s_waitcnt lgkmcnt(0)
	v_add_f32_e32 v98, v98, v125
	ds_bpermute_b32 v125, v117, v98
	s_waitcnt lgkmcnt(0)
	v_add_f32_e32 v98, v98, v125
	ds_bpermute_b32 v125, v118, v98
	s_waitcnt lgkmcnt(0)
	v_add_f32_e32 v80, v98, v125
	v_fmamk_f32 v80, v80, 0x3a800000, v119
	v_mul_f32_e32 v98, 0x4f800000, v80
	v_cmp_gt_f32_e32 vcc, s36, v80
	s_nop 1
	v_cndmask_b32_e32 v98, v80, v98, vcc
	v_sqrt_f32_e32 v125, v98
	v_lshlrev_b32_e32 v80, 16, v81
	v_and_b32_e32 v81, 0xffff0000, v81
	v_add_u32_e32 v137, -1, v125
	v_fma_f32 v138, -v137, v125, v98
	v_cmp_ge_f32_e64 s[2:3], 0, v138
	v_add_u32_e32 v138, 1, v125
	s_nop 0
	v_cndmask_b32_e64 v137, v125, v137, s[2:3]
	v_fma_f32 v125, -v138, v125, v98
	v_cmp_lt_f32_e64 s[2:3], 0, v125
	s_nop 1
	v_cndmask_b32_e64 v125, v137, v138, s[2:3]
	v_mul_f32_e32 v137, 0x37800000, v125
	v_cndmask_b32_e32 v125, v125, v137, vcc
	v_cmp_class_f32_e32 vcc, v98, v120
	v_and_b32_e32 v137, 0xffff0000, v82
	v_lshlrev_b32_e32 v82, 16, v83
	v_cndmask_b32_e32 v98, v125, v98, vcc
	v_div_scale_f32 v125, s[2:3], v98, v98, 1.0
	v_rcp_f32_e32 v138, v125
	v_and_b32_e32 v83, 0xffff0000, v83
	v_fma_f32 v139, -v125, v138, 1.0
	v_fmac_f32_e32 v138, v139, v138
	v_div_scale_f32 v139, vcc, 1.0, v98, 1.0
	v_mul_f32_e32 v140, v139, v138
	v_fma_f32 v141, -v125, v140, v139
	v_fmac_f32_e32 v140, v141, v138
	v_fma_f32 v125, -v125, v140, v139
	v_div_fmas_f32 v125, v125, v138, v140
	v_div_fixup_f32 v98, v125, v98, 1.0
	v_mov_b32_e32 v138, v126
	v_mov_b32_e32 v139, v92
	v_mov_b32_e32 v92, v127
	v_pk_mul_f32 v[138:139], v[98:99], v[138:139] op_sel_hi:[0,1]
	v_pk_mul_f32 v[92:93], v[98:99], v[92:93] op_sel_hi:[0,1]
	v_pk_mul_f32 v[88:89], v[98:99], v[88:89] op_sel_hi:[0,1]
	v_mov_b32_e32 v125, v121
	v_pk_fma_f32 v[84:85], v[62:63], v[92:93], v[84:85]
	v_pk_fma_f32 v[92:93], v[60:61], v[138:139], v[128:129]
	v_mov_b32_e32 v126, v130
	v_mov_b32_e32 v127, v94
	v_mov_b32_e32 v94, v131
	v_pk_fma_f32 v[88:89], v[34:35], v[88:89], v[80:81]
	v_pk_mul_f32 v[80:81], v[98:99], v[124:125] op_sel_hi:[0,1]
	v_pk_mul_f32 v[90:91], v[98:99], v[90:91] op_sel_hi:[0,1]
	v_pk_mul_f32 v[126:127], v[98:99], v[126:127] op_sel_hi:[0,1]
	v_pk_mul_f32 v[94:95], v[98:99], v[94:95] op_sel_hi:[0,1]
	v_pk_fma_f32 v[90:91], v[58:59], v[90:91], v[82:83]
	v_pk_fma_f32 v[124:125], v[56:57], v[80:81], v[136:137]
	v_pk_mul_f32 v[80:81], v[84:85], v[84:85]
	v_pk_mul_f32 v[82:83], v[92:93], v[92:93]
	v_pk_fma_f32 v[86:87], v[22:23], v[94:95], v[86:87]
	v_pk_fma_f32 v[94:95], v[20:21], v[126:127], v[132:133]
	v_pk_mov_b32 v[126:127], v[82:83], v[80:81] op_sel:[1,0]
	v_mov_b32_e32 v83, v81
	v_pk_mul_f32 v[122:123], v[98:99], v[122:123] op_sel_hi:[0,1]
	v_pk_add_f32 v[80:81], v[126:127], v[82:83]
	v_pk_fma_f32 v[122:123], v[32:33], v[122:123], v[134:135]
	v_pk_add_f32 v[80:81], v[80:81], v[80:81] op_sel_hi:[0,1]
	v_pk_mul_f32 v[82:83], v[86:87], v[86:87]
	v_pk_mul_f32 v[126:127], v[94:95], v[94:95]
	v_mul_f32_e32 v80, v122, v122
	v_pk_mov_b32 v[128:129], v[126:127], v[82:83] op_sel:[1,0]
	v_mov_b32_e32 v127, v83
	v_pk_add_f32 v[82:83], v[128:129], v[126:127]
	v_pk_fma_f32 v[126:127], v[122:123], v[122:123], v[80:81] op_sel_hi:[1,1,0]
	v_mul_f32_e32 v80, v88, v88
	v_pk_add_f32 v[82:83], v[82:83], v[82:83] op_sel_hi:[0,1]
	v_pk_fma_f32 v[128:129], v[88:89], v[88:89], v[80:81] op_sel_hi:[1,1,0]
	v_mul_f32_e32 v126, v124, v124
	v_mul_f32_e32 v128, v125, v125
	v_mul_f32_e32 v80, v90, v90
	v_mul_f32_e32 v82, v91, v91
	v_pk_add_f32 v[126:127], v[126:127], v[128:129]
	v_pk_add_f32 v[80:81], v[80:81], v[82:83]
	v_cvt_pk_bf16_f32 v82, v94, v95
	v_pk_add_f32 v[80:81], v[126:127], v[80:81]
	v_lshl_add_u64 v[126:127], s[10:11], 0, v[96:97]
	v_add_f32_e32 v80, v80, v81
	ds_bpermute_b32 v81, v109, v80
	v_add_co_u32_e32 v126, vcc, s37, v126
	v_cvt_pk_bf16_f32 v83, v86, v87
	s_nop 0
	v_addc_co_u32_e32 v127, vcc, 0, v127, vcc
	s_waitcnt lgkmcnt(0)
	v_add_f32_e32 v80, v80, v81
	ds_bpermute_b32 v81, v114, v80
	s_waitcnt lgkmcnt(0)
	v_add_f32_e32 v80, v80, v81
	ds_bpermute_b32 v81, v115, v80
	s_waitcnt lgkmcnt(0)
	v_add_f32_e32 v80, v80, v81
	ds_bpermute_b32 v81, v116, v80
	s_waitcnt lgkmcnt(0)
	v_add_f32_e32 v98, v80, v81
	ds_bpermute_b32 v121, v117, v98
	v_cvt_pk_bf16_f32 v80, v92, v93
	v_cvt_pk_bf16_f32 v81, v84, v85
	global_store_dwordx4 v[126:127], v[80:83], off nt
	s_waitcnt lgkmcnt(0)
	v_add_f32_e32 v98, v98, v121
	ds_bpermute_b32 v121, v118, v98
	v_cvt_pk_bf16_f32 v80, v122, v123
	v_cvt_pk_bf16_f32 v81, v88, v89
	s_waitcnt lgkmcnt(0)
	v_add_f32_e32 v98, v98, v121
	v_fmamk_f32 v98, v98, 0x3a800000, v119
	v_mul_f32_e32 v121, 0x4f800000, v98
	v_cmp_gt_f32_e32 vcc, s36, v98
	s_nop 1
	v_cndmask_b32_e32 v98, v98, v121, vcc
	v_sqrt_f32_e32 v121, v98
	s_nop 0
	v_add_u32_e32 v82, -1, v121
	v_fma_f32 v83, -v82, v121, v98
	v_cmp_ge_f32_e64 s[2:3], 0, v83
	v_add_u32_e32 v83, 1, v121
	s_nop 0
	v_cndmask_b32_e64 v82, v121, v82, s[2:3]
	v_fma_f32 v121, -v83, v121, v98
	v_cmp_lt_f32_e64 s[2:3], 0, v121
	s_nop 1
	v_cndmask_b32_e64 v82, v82, v83, s[2:3]
	v_mul_f32_e32 v83, 0x37800000, v82
	v_cndmask_b32_e32 v82, v82, v83, vcc
	v_cmp_class_f32_e32 vcc, v98, v120
	v_cvt_pk_bf16_f32 v83, v90, v91
	s_nop 0
	v_cndmask_b32_e32 v98, v82, v98, vcc
	v_div_scale_f32 v121, s[2:3], v98, v98, 1.0
	v_rcp_f32_e32 v128, v121
	v_cvt_pk_bf16_f32 v82, v124, v125
	global_store_dwordx4 v[126:127], v[80:83], off offset:1024 nt
	v_lshl_add_u64 v[126:127], s[8:9], 0, v[96:97]
	s_nop 0
	v_fma_f32 v80, -v121, v128, 1.0
	v_fmac_f32_e32 v128, v80, v128
	v_div_scale_f32 v80, vcc, 1.0, v98, 1.0
	v_mul_f32_e32 v81, v80, v128
	v_fma_f32 v82, -v121, v81, v80
	v_fmac_f32_e32 v81, v82, v128
	v_fma_f32 v80, -v121, v81, v80
	v_div_fmas_f32 v80, v80, v128, v81
	v_div_fixup_f32 v98, v80, v98, 1.0
	v_pk_mul_f32 v[80:81], v[92:93], v[98:99] op_sel_hi:[1,0]
	v_pk_mul_f32 v[82:83], v[84:85], v[98:99] op_sel_hi:[1,0]
	v_pk_mul_f32 v[84:85], v[94:95], v[98:99] op_sel_hi:[1,0]
	v_pk_fma_f32 v[82:83], v[78:79], v[82:83], v[38:39]
	v_pk_fma_f32 v[80:81], v[76:77], v[80:81], v[36:37]
	v_pk_mul_f32 v[86:87], v[86:87], v[98:99] op_sel_hi:[1,0]
	v_pk_fma_f32 v[84:85], v[64:65], v[84:85], v[24:25]
	v_pk_fma_f32 v[86:87], v[66:67], v[86:87], v[26:27]
	v_cvt_pk_bf16_f32 v80, v80, v81
	v_cvt_pk_bf16_f32 v81, v82, v83
	v_cvt_pk_bf16_f32 v82, v84, v85
	v_add_co_u32_e32 v84, vcc, s38, v126
	v_cvt_pk_bf16_f32 v83, v86, v87
	s_nop 0
	v_addc_co_u32_e32 v85, vcc, 0, v127, vcc
	global_store_dwordx4 v[84:85], v[80:83], off
	v_pk_mul_f32 v[86:87], v[124:125], v[98:99] op_sel_hi:[1,0]
	s_nop 0
	v_pk_mul_f32 v[80:81], v[122:123], v[98:99] op_sel_hi:[1,0]
	v_pk_mul_f32 v[82:83], v[88:89], v[98:99] op_sel_hi:[1,0]
	v_pk_mul_f32 v[88:89], v[90:91], v[98:99] op_sel_hi:[1,0]
	v_pk_fma_f32 v[82:83], v[70:71], v[82:83], v[30:31]
	v_pk_fma_f32 v[80:81], v[68:69], v[80:81], v[28:29]
	v_pk_fma_f32 v[88:89], v[74:75], v[88:89], v[18:19]
	v_pk_fma_f32 v[86:87], v[72:73], v[86:87], v[16:17]
	v_cvt_pk_bf16_f32 v80, v80, v81
	v_cvt_pk_bf16_f32 v81, v82, v83
	v_cvt_pk_bf16_f32 v82, v86, v87
	v_cvt_pk_bf16_f32 v83, v88, v89
	global_store_dwordx4 v[84:85], v[80:83], off offset:1024
	s_cbranch_scc1 .LBB0_681
	s_ashr_i32 s2, s22, 13
	s_cmp_eq_u32 s2, s40
	s_cbranch_scc1 .LBB0_689
	s_mul_i32 s7, s2, 0x6000
	s_mul_hi_i32 s3, s2, 0x6000
	s_add_u32 s34, s46, s7
	s_addc_u32 s35, s47, s3
	v_lshlrev_b32_e32 v98, 4, v108
	v_lshl_add_u64 v[16:17], s[34:35], 0, v[98:99]
	v_add_co_u32_e32 v26, vcc, s24, v16
	v_lshl_add_u64 v[18:19], v[16:17], 0, s[16:17]
	s_nop 0
	v_addc_co_u32_e32 v27, vcc, 0, v17, vcc
	v_lshl_add_u64 v[24:25], v[16:17], 0, s[18:19]
	global_load_dwordx4 v[20:23], v[110:111], off offset:16
	global_load_dwordx4 v[60:63], v[110:111], off
	global_load_dwordx4 v[64:67], v[26:27], off
	global_load_dwordx4 v[32:35], v[18:19], off offset:16
	global_load_dwordx4 v[56:59], v[24:25], off offset:16
	global_load_dwordx4 v[68:71], v[110:111], off offset:2064
	global_load_dwordx4 v[72:75], v[110:111], off offset:2048
	global_load_dwordx4 v[76:79], v[18:19], off offset:2048
	global_load_dwordx4 v[80:83], v[24:25], off offset:2064
	global_load_dwordx4 v[84:87], v[24:25], off offset:2048
	global_load_dwordx4 v[88:91], v[112:113], off offset:16
	global_load_dwordx4 v[92:95], v[112:113], off
	global_load_dwordx4 v[122:125], v[18:19], off offset:2064
	v_add_co_u32_e32 v18, vcc, s25, v16
	v_lshl_add_u64 v[28:29], v[16:17], 0, s[20:21]
	s_nop 0
	v_addc_co_u32_e32 v19, vcc, 0, v17, vcc
	v_add_co_u32_e32 v36, vcc, s27, v16
	global_load_dwordx4 v[126:129], v[18:19], off
	global_load_dwordx4 v[130:133], v[112:113], off offset:2064
	global_load_dwordx4 v[134:137], v[112:113], off offset:2048
	v_addc_co_u32_e32 v37, vcc, 0, v17, vcc
	global_load_dwordx4 v[16:19], v[28:29], off offset:2064 nt
	global_load_dwordx4 v[24:27], v[28:29], off offset:16 nt
	s_nop 0
	global_load_dwordx4 v[28:31], v[28:29], off offset:2048 nt
	s_nop 0
	global_load_dwordx4 v[36:39], v[36:37], off nt
	s_mov_b32 s40, s2
	s_waitcnt vmcnt(15)
	v_pk_add_f32 v[138:139], v[58:59], 1.0 op_sel_hi:[1,0]
	v_pk_add_f32 v[140:141], v[56:57], 1.0 op_sel_hi:[1,0]
	v_pk_mul_f32 v[22:23], v[22:23], v[34:35]
	v_pk_mul_f32 v[20:21], v[20:21], v[32:33]
	s_waitcnt vmcnt(12)
	v_pk_mul_f32 v[34:35], v[74:75], v[78:79]
	v_pk_mul_f32 v[32:33], v[72:73], v[76:77]
	s_waitcnt vmcnt(10)
	v_pk_add_f32 v[74:75], v[84:85], 1.0 op_sel_hi:[1,0]
	v_pk_add_f32 v[76:77], v[82:83], 1.0 op_sel_hi:[1,0]
	v_pk_add_f32 v[72:73], v[86:87], 1.0 op_sel_hi:[1,0]
	s_waitcnt vmcnt(7)
	v_pk_mul_f32 v[56:57], v[68:69], v[122:123]
	v_pk_add_f32 v[78:79], v[80:81], 1.0 op_sel_hi:[1,0]
	s_waitcnt vmcnt(6)
	v_pk_add_f32 v[80:81], v[126:127], 1.0 op_sel_hi:[1,0]
	s_waitcnt vmcnt(4)
	v_pk_mul_f32 v[68:69], v[134:135], v[74:75]
	v_pk_mul_f32 v[74:75], v[132:133], v[76:77]
	v_pk_add_f32 v[76:77], v[128:129], 1.0 op_sel_hi:[1,0]
	v_pk_mul_f32 v[58:59], v[70:71], v[124:125]
	v_pk_mul_f32 v[62:63], v[62:63], v[66:67]
	v_pk_mul_f32 v[60:61], v[60:61], v[64:65]
	v_pk_mul_f32 v[66:67], v[90:91], v[138:139]
	v_pk_mul_f32 v[64:65], v[88:89], v[140:141]
	v_pk_mul_f32 v[70:71], v[136:137], v[72:73]
	v_pk_mul_f32 v[72:73], v[130:131], v[78:79]
	v_pk_mul_f32 v[78:79], v[94:95], v[76:77]
	v_pk_mul_f32 v[76:77], v[92:93], v[80:81]
.LBB0_689:
	v_mov_b64_e32 v[82:83], v[14:15]
	v_mov_b64_e32 v[90:91], v[10:11]
	v_mov_b64_e32 v[86:87], v[6:7]
	v_mov_b64_e32 v[94:95], v[2:3]
	s_cmp_ge_i32 s6, s26
	v_mov_b64_e32 v[80:81], v[12:13]
	v_mov_b64_e32 v[88:89], v[8:9]
	v_mov_b64_e32 v[84:85], v[4:5]
	v_mov_b64_e32 v[92:93], v[0:1]
	s_cbranch_scc1 .LBB0_680
	s_ashr_i32 s7, s6, 31
	s_lshl_b64 s[2:3], s[6:7], 11
	v_lshl_add_u64 v[124:125], v[106:107], 0, s[2:3]
	v_lshl_add_u64 v[122:123], v[104:105], 0, s[2:3]
	global_load_dwordx4 v[84:87], v[124:125], off nt
	global_load_dwordx4 v[92:95], v[124:125], off offset:1024 nt
	global_load_dwordx4 v[80:83], v[122:123], off nt
	global_load_dwordx4 v[88:91], v[122:123], off offset:1024 nt
	s_branch .LBB0_680

.LBB0_1185:
	v_lshlrev_b32_e32 v127, 16, v13
	v_lshlrev_b32_e32 v126, 16, v12
	v_and_b32_e32 v13, 0xffff0000, v13
	v_and_b32_e32 v12, 0xffff0000, v12
	v_lshlrev_b32_e32 v131, 16, v15
	v_lshlrev_b32_e32 v130, 16, v14
	v_and_b32_e32 v15, 0xffff0000, v15
	v_and_b32_e32 v14, 0xffff0000, v14
	v_lshlrev_b32_e32 v122, 16, v8
	v_and_b32_e32 v123, 0xffff0000, v8
	v_lshlrev_b32_e32 v124, 16, v10
	v_pk_mul_f32 v[128:129], v[12:13], v[12:13]
	v_pk_mul_f32 v[132:133], v[14:15], v[14:15]
	v_lshlrev_b32_e32 v8, 16, v9
	v_pk_fma_f32 v[128:129], v[126:127], v[126:127], v[128:129]
	v_pk_fma_f32 v[132:133], v[130:131], v[130:131], v[132:133]
	v_mul_f32_e32 v125, v122, v122
	v_mul_f32_e32 v135, v123, v123
	v_and_b32_e32 v9, 0xffff0000, v9
	v_mul_f32_e32 v98, v8, v8
	v_mov_b32_e32 v134, v124
	v_and_b32_e32 v121, 0xffff0000, v10
	v_lshlrev_b32_e32 v10, 16, v11
	v_and_b32_e32 v11, 0xffff0000, v11
	v_pk_add_f32 v[128:129], v[128:129], v[128:129] op_sel_hi:[0,1]
	v_pk_add_f32 v[132:133], v[132:133], v[132:133] op_sel_hi:[0,1]
	v_pk_fma_f32 v[136:137], v[8:9], v[8:9], v[98:99] op_sel_hi:[1,1,0]
	v_pk_add_f32 v[134:135], v[124:125], v[134:135]
	v_mul_f32_e32 v136, v121, v121
	v_mul_f32_e32 v128, v10, v10
	v_mul_f32_e32 v132, v11, v11
	v_mul_f32_e32 v138, v124, v124
	v_mov_b32_e32 v139, v135
	v_pk_add_f32 v[134:135], v[138:139], v[136:137]
	v_pk_add_f32 v[128:129], v[128:129], v[132:133]
	v_lshlrev_b32_e32 v136, 16, v2
	v_pk_add_f32 v[128:129], v[134:135], v[128:129]
	v_lshlrev_b32_e32 v134, 16, v0
	v_add_f32_e32 v98, v128, v129
	ds_bpermute_b32 v125, v109, v98
	v_and_b32_e32 v135, 0xffff0000, v0
	v_lshlrev_b32_e32 v128, 16, v4
	v_and_b32_e32 v129, 0xffff0000, v4
	v_lshlrev_b32_e32 v4, 16, v5
	s_waitcnt lgkmcnt(0)
	v_add_f32_e32 v98, v98, v125
	ds_bpermute_b32 v125, v114, v98
	v_and_b32_e32 v5, 0xffff0000, v5
	v_lshlrev_b32_e32 v132, 16, v6
	v_and_b32_e32 v133, 0xffff0000, v6
	v_lshlrev_b32_e32 v6, 16, v7
	s_waitcnt lgkmcnt(0)
	v_add_f32_e32 v98, v98, v125
	ds_bpermute_b32 v125, v115, v98
	v_and_b32_e32 v7, 0xffff0000, v7
	s_ashr_i32 s23, s22, 31
	s_lshl_b64 s[22:23], s[22:23], 11
	s_waitcnt lgkmcnt(0)
	v_add_f32_e32 v98, v98, v125
	ds_bpermute_b32 v125, v116, v98
	s_waitcnt lgkmcnt(0)
	v_add_f32_e32 v98, v98, v125
	ds_bpermute_b32 v125, v117, v98
	s_waitcnt lgkmcnt(0)
	v_add_f32_e32 v98, v98, v125
	ds_bpermute_b32 v125, v118, v98
	s_waitcnt lgkmcnt(0)
	v_add_f32_e32 v0, v98, v125
	v_fmamk_f32 v0, v0, 0x3a800000, v119
	v_mul_f32_e32 v98, 0x4f800000, v0
	v_cmp_gt_f32_e32 vcc, s27, v0
	s_nop 1
	v_cndmask_b32_e32 v98, v0, v98, vcc
	v_sqrt_f32_e32 v125, v98
	v_lshlrev_b32_e32 v0, 16, v1
	v_and_b32_e32 v1, 0xffff0000, v1
	v_add_u32_e32 v137, -1, v125
	v_fma_f32 v138, -v137, v125, v98
	v_cmp_ge_f32_e64 s[2:3], 0, v138
	v_add_u32_e32 v138, 1, v125
	s_nop 0
	v_cndmask_b32_e64 v137, v125, v137, s[2:3]
	v_fma_f32 v125, -v138, v125, v98
	v_cmp_lt_f32_e64 s[2:3], 0, v125
	s_nop 1
	v_cndmask_b32_e64 v125, v137, v138, s[2:3]
	v_mul_f32_e32 v137, 0x37800000, v125
	v_cndmask_b32_e32 v125, v125, v137, vcc
	v_cmp_class_f32_e32 vcc, v98, v120
	v_and_b32_e32 v137, 0xffff0000, v2
	v_lshlrev_b32_e32 v2, 16, v3
	v_cndmask_b32_e32 v98, v125, v98, vcc
	v_div_scale_f32 v125, s[2:3], v98, v98, 1.0
	v_rcp_f32_e32 v138, v125
	v_and_b32_e32 v3, 0xffff0000, v3
	v_fma_f32 v139, -v125, v138, 1.0
	v_fmac_f32_e32 v138, v139, v138
	v_div_scale_f32 v139, vcc, 1.0, v98, 1.0
	v_mul_f32_e32 v140, v139, v138
	v_fma_f32 v141, -v125, v140, v139
	v_fmac_f32_e32 v140, v141, v138
	v_fma_f32 v125, -v125, v140, v139
	v_div_fmas_f32 v125, v125, v138, v140
	v_div_fixup_f32 v98, v125, v98, 1.0
	v_mov_b32_e32 v138, v126
	v_mov_b32_e32 v139, v12
	v_mov_b32_e32 v12, v127
	v_pk_mul_f32 v[138:139], v[98:99], v[138:139] op_sel_hi:[0,1]
	v_pk_mul_f32 v[12:13], v[98:99], v[12:13] op_sel_hi:[0,1]
	v_pk_mul_f32 v[8:9], v[98:99], v[8:9] op_sel_hi:[0,1]
	v_mov_b32_e32 v125, v121
	v_pk_fma_f32 v[4:5], v[62:63], v[12:13], v[4:5]
	v_pk_fma_f32 v[12:13], v[60:61], v[138:139], v[128:129]
	v_mov_b32_e32 v126, v130
	v_mov_b32_e32 v127, v14
	v_mov_b32_e32 v14, v131
	v_pk_fma_f32 v[8:9], v[38:39], v[8:9], v[0:1]
	v_pk_mul_f32 v[0:1], v[98:99], v[124:125] op_sel_hi:[0,1]
	v_pk_mul_f32 v[10:11], v[98:99], v[10:11] op_sel_hi:[0,1]
	v_pk_mul_f32 v[126:127], v[98:99], v[126:127] op_sel_hi:[0,1]
	v_pk_mul_f32 v[14:15], v[98:99], v[14:15] op_sel_hi:[0,1]
	v_pk_fma_f32 v[10:11], v[58:59], v[10:11], v[2:3]
	v_pk_fma_f32 v[124:125], v[56:57], v[0:1], v[136:137]
	v_pk_mul_f32 v[0:1], v[4:5], v[4:5]
	v_pk_mul_f32 v[2:3], v[12:13], v[12:13]
	v_pk_fma_f32 v[6:7], v[30:31], v[14:15], v[6:7]
	v_pk_fma_f32 v[14:15], v[28:29], v[126:127], v[132:133]
	v_pk_mov_b32 v[126:127], v[2:3], v[0:1] op_sel:[1,0]
	v_mov_b32_e32 v3, v1
	v_pk_mul_f32 v[122:123], v[98:99], v[122:123] op_sel_hi:[0,1]
	v_pk_add_f32 v[0:1], v[126:127], v[2:3]
	v_pk_fma_f32 v[122:123], v[36:37], v[122:123], v[134:135]
	v_pk_add_f32 v[0:1], v[0:1], v[0:1] op_sel_hi:[0,1]
	v_pk_mul_f32 v[2:3], v[6:7], v[6:7]
	v_pk_mul_f32 v[126:127], v[14:15], v[14:15]
	v_mul_f32_e32 v0, v122, v122
	v_pk_mov_b32 v[128:129], v[126:127], v[2:3] op_sel:[1,0]
	v_mov_b32_e32 v127, v3
	v_pk_add_f32 v[2:3], v[128:129], v[126:127]
	v_pk_fma_f32 v[126:127], v[122:123], v[122:123], v[0:1] op_sel_hi:[1,1,0]
	v_mul_f32_e32 v0, v8, v8
	v_pk_add_f32 v[2:3], v[2:3], v[2:3] op_sel_hi:[0,1]
	v_pk_fma_f32 v[128:129], v[8:9], v[8:9], v[0:1] op_sel_hi:[1,1,0]
	v_mul_f32_e32 v126, v124, v124
	v_mul_f32_e32 v128, v125, v125
	v_mul_f32_e32 v0, v10, v10
	v_mul_f32_e32 v2, v11, v11
	v_pk_add_f32 v[126:127], v[126:127], v[128:129]
	v_pk_add_f32 v[0:1], v[0:1], v[2:3]
	v_cvt_pk_bf16_f32 v2, v14, v15
	v_pk_add_f32 v[0:1], v[126:127], v[0:1]
	v_lshl_add_u64 v[126:127], v[100:101], 0, s[22:23]
	v_add_f32_e32 v0, v0, v1
	ds_bpermute_b32 v1, v109, v0
	v_cvt_pk_bf16_f32 v3, v6, v7
	s_waitcnt lgkmcnt(0)
	v_add_f32_e32 v0, v0, v1
	ds_bpermute_b32 v1, v114, v0
	s_waitcnt lgkmcnt(0)
	v_add_f32_e32 v0, v0, v1
	ds_bpermute_b32 v1, v115, v0
	s_waitcnt lgkmcnt(0)
	v_add_f32_e32 v0, v0, v1
	ds_bpermute_b32 v1, v116, v0
	s_waitcnt lgkmcnt(0)
	v_add_f32_e32 v0, v0, v1
	ds_bpermute_b32 v1, v117, v0
	s_waitcnt lgkmcnt(0)
	v_add_f32_e32 v98, v0, v1
	ds_bpermute_b32 v121, v118, v98
	v_cvt_pk_bf16_f32 v0, v12, v13
	v_cvt_pk_bf16_f32 v1, v4, v5
	global_store_dwordx4 v[126:127], v[0:3], off nt
	s_waitcnt lgkmcnt(0)
	v_add_f32_e32 v98, v98, v121
	v_fmamk_f32 v98, v98, 0x3a800000, v119
	v_mul_f32_e32 v121, 0x4f800000, v98
	v_cmp_gt_f32_e32 vcc, s27, v98
	v_cvt_pk_bf16_f32 v0, v122, v123
	v_cvt_pk_bf16_f32 v1, v8, v9
	v_cndmask_b32_e32 v98, v98, v121, vcc
	v_sqrt_f32_e32 v121, v98
	s_nop 0
	v_add_u32_e32 v2, -1, v121
	v_fma_f32 v3, -v2, v121, v98
	v_cmp_ge_f32_e64 s[2:3], 0, v3
	v_add_u32_e32 v3, 1, v121
	s_nop 0
	v_cndmask_b32_e64 v2, v121, v2, s[2:3]
	v_fma_f32 v121, -v3, v121, v98
	v_cmp_lt_f32_e64 s[2:3], 0, v121
	s_nop 1
	v_cndmask_b32_e64 v2, v2, v3, s[2:3]
	v_mul_f32_e32 v3, 0x37800000, v2
	v_cndmask_b32_e32 v2, v2, v3, vcc
	v_cmp_class_f32_e32 vcc, v98, v120
	v_cvt_pk_bf16_f32 v3, v10, v11
	s_nop 0
	v_cndmask_b32_e32 v98, v2, v98, vcc
	v_div_scale_f32 v121, s[2:3], v98, v98, 1.0
	v_rcp_f32_e32 v128, v121
	v_cvt_pk_bf16_f32 v2, v124, v125
	global_store_dwordx4 v[126:127], v[0:3], off offset:1024 nt
	v_lshl_add_u64 v[126:127], v[102:103], 0, s[22:23]
	s_nop 0
	v_fma_f32 v0, -v121, v128, 1.0
	v_fmac_f32_e32 v128, v0, v128
	v_div_scale_f32 v0, vcc, 1.0, v98, 1.0
	v_mul_f32_e32 v1, v0, v128
	v_fma_f32 v2, -v121, v1, v0
	v_fmac_f32_e32 v1, v2, v128
	v_fma_f32 v0, -v121, v1, v0
	v_div_fmas_f32 v0, v0, v128, v1
	v_div_fixup_f32 v98, v0, v98, 1.0
	v_pk_mul_f32 v[0:1], v[12:13], v[98:99] op_sel_hi:[1,0]
	v_pk_mul_f32 v[2:3], v[4:5], v[98:99] op_sel_hi:[1,0]
	v_pk_mul_f32 v[4:5], v[14:15], v[98:99] op_sel_hi:[1,0]
	v_pk_mul_f32 v[6:7], v[6:7], v[98:99] op_sel_hi:[1,0]
	s_waitcnt vmcnt(2)
	v_pk_fma_f32 v[2:3], v[66:67], v[2:3], v[34:35]
	v_pk_fma_f32 v[0:1], v[64:65], v[0:1], v[32:33]
	v_pk_fma_f32 v[6:7], v[70:71], v[6:7], v[22:23]
	v_pk_fma_f32 v[4:5], v[68:69], v[4:5], v[20:21]
	v_cvt_pk_bf16_f32 v0, v0, v1
	v_cvt_pk_bf16_f32 v1, v2, v3
	v_cvt_pk_bf16_f32 v2, v4, v5
	v_cvt_pk_bf16_f32 v3, v6, v7
	global_store_dwordx4 v[126:127], v[0:3], off
	v_pk_mul_f32 v[4:5], v[124:125], v[98:99] op_sel_hi:[1,0]
	v_pk_mul_f32 v[6:7], v[10:11], v[98:99] op_sel_hi:[1,0]
	v_pk_mul_f32 v[0:1], v[122:123], v[98:99] op_sel_hi:[1,0]
	v_pk_mul_f32 v[2:3], v[8:9], v[98:99] op_sel_hi:[1,0]
	v_pk_fma_f32 v[0:1], v[72:73], v[0:1], v[24:25]
	v_pk_fma_f32 v[2:3], v[74:75], v[2:3], v[26:27]
	v_pk_fma_f32 v[6:7], v[78:79], v[6:7], v[18:19]
	v_pk_fma_f32 v[4:5], v[76:77], v[4:5], v[16:17]
	v_cvt_pk_bf16_f32 v0, v0, v1
	v_cvt_pk_bf16_f32 v1, v2, v3
	v_cvt_pk_bf16_f32 v2, v4, v5
	v_cvt_pk_bf16_f32 v3, v6, v7
	global_store_dwordx4 v[126:127], v[0:3], off offset:1024
	v_mov_b64_e32 v[4:5], v[84:85]
	v_mov_b64_e32 v[8:9], v[88:89]
	v_mov_b64_e32 v[0:1], v[92:93]
	v_mov_b64_e32 v[12:13], v[80:81]
	v_mov_b64_e32 v[2:3], v[94:95]
	v_mov_b64_e32 v[6:7], v[86:87]
	v_mov_b64_e32 v[10:11], v[90:91]
	v_mov_b64_e32 v[14:15], v[82:83]

.LBB0_1191:
	v_lshlrev_b32_e32 v127, 16, v93
	v_lshlrev_b32_e32 v126, 16, v92
	v_and_b32_e32 v93, 0xffff0000, v93
	v_and_b32_e32 v92, 0xffff0000, v92
	v_lshlrev_b32_e32 v131, 16, v95
	v_lshlrev_b32_e32 v130, 16, v94
	v_and_b32_e32 v95, 0xffff0000, v95
	v_and_b32_e32 v94, 0xffff0000, v94
	v_lshlrev_b32_e32 v122, 16, v88
	v_and_b32_e32 v123, 0xffff0000, v88
	v_lshlrev_b32_e32 v124, 16, v90
	v_pk_mul_f32 v[128:129], v[92:93], v[92:93]
	v_pk_mul_f32 v[132:133], v[94:95], v[94:95]
	v_lshlrev_b32_e32 v88, 16, v89
	v_pk_fma_f32 v[128:129], v[126:127], v[126:127], v[128:129]
	v_pk_fma_f32 v[132:133], v[130:131], v[130:131], v[132:133]
	v_mul_f32_e32 v125, v122, v122
	v_mul_f32_e32 v135, v123, v123
	v_and_b32_e32 v89, 0xffff0000, v89
	v_mul_f32_e32 v98, v88, v88
	v_mov_b32_e32 v134, v124
	v_and_b32_e32 v121, 0xffff0000, v90
	v_lshlrev_b32_e32 v90, 16, v91
	v_and_b32_e32 v91, 0xffff0000, v91
	v_pk_add_f32 v[128:129], v[128:129], v[128:129] op_sel_hi:[0,1]
	v_pk_add_f32 v[132:133], v[132:133], v[132:133] op_sel_hi:[0,1]
	v_pk_fma_f32 v[136:137], v[88:89], v[88:89], v[98:99] op_sel_hi:[1,1,0]
	v_pk_add_f32 v[134:135], v[124:125], v[134:135]
	v_mul_f32_e32 v136, v121, v121
	v_mul_f32_e32 v128, v90, v90
	v_mul_f32_e32 v132, v91, v91
	v_mul_f32_e32 v138, v124, v124
	v_mov_b32_e32 v139, v135
	v_pk_add_f32 v[134:135], v[138:139], v[136:137]
	v_pk_add_f32 v[128:129], v[128:129], v[132:133]
	v_lshlrev_b32_e32 v136, 16, v82
	v_pk_add_f32 v[128:129], v[134:135], v[128:129]
	v_lshlrev_b32_e32 v134, 16, v80
	v_add_f32_e32 v98, v128, v129
	ds_bpermute_b32 v125, v109, v98
	v_and_b32_e32 v135, 0xffff0000, v80
	v_lshlrev_b32_e32 v128, 16, v84
	v_and_b32_e32 v129, 0xffff0000, v84
	v_lshlrev_b32_e32 v84, 16, v85
	s_waitcnt lgkmcnt(0)
	v_add_f32_e32 v98, v98, v125
	ds_bpermute_b32 v125, v114, v98
	v_and_b32_e32 v85, 0xffff0000, v85
	v_lshlrev_b32_e32 v132, 16, v86
	v_and_b32_e32 v133, 0xffff0000, v86
	v_lshlrev_b32_e32 v86, 16, v87
	s_waitcnt lgkmcnt(0)
	v_add_f32_e32 v98, v98, v125
	ds_bpermute_b32 v125, v115, v98
	v_and_b32_e32 v87, 0xffff0000, v87
	s_add_i32 s22, s6, -2
	s_cmp_ge_i32 s22, s26
	s_waitcnt lgkmcnt(0)
	v_add_f32_e32 v98, v98, v125
	ds_bpermute_b32 v125, v116, v98
	s_waitcnt lgkmcnt(0)
	v_add_f32_e32 v98, v98, v125
	ds_bpermute_b32 v125, v117, v98
	s_waitcnt lgkmcnt(0)
	v_add_f32_e32 v98, v98, v125
	ds_bpermute_b32 v125, v118, v98
	s_waitcnt lgkmcnt(0)
	v_add_f32_e32 v80, v98, v125
	v_fmamk_f32 v80, v80, 0x3a800000, v119
	v_mul_f32_e32 v98, 0x4f800000, v80
	v_cmp_gt_f32_e32 vcc, s27, v80
	s_nop 1
	v_cndmask_b32_e32 v98, v80, v98, vcc
	v_sqrt_f32_e32 v125, v98
	v_lshlrev_b32_e32 v80, 16, v81
	v_and_b32_e32 v81, 0xffff0000, v81
	v_add_u32_e32 v137, -1, v125
	v_fma_f32 v138, -v137, v125, v98
	v_cmp_ge_f32_e64 s[2:3], 0, v138
	v_add_u32_e32 v138, 1, v125
	s_nop 0
	v_cndmask_b32_e64 v137, v125, v137, s[2:3]
	v_fma_f32 v125, -v138, v125, v98
	v_cmp_lt_f32_e64 s[2:3], 0, v125
	s_nop 1
	v_cndmask_b32_e64 v125, v137, v138, s[2:3]
	v_mul_f32_e32 v137, 0x37800000, v125
	v_cndmask_b32_e32 v125, v125, v137, vcc
	v_cmp_class_f32_e32 vcc, v98, v120
	v_and_b32_e32 v137, 0xffff0000, v82
	v_lshlrev_b32_e32 v82, 16, v83
	v_cndmask_b32_e32 v98, v125, v98, vcc
	v_div_scale_f32 v125, s[2:3], v98, v98, 1.0
	v_rcp_f32_e32 v138, v125
	v_and_b32_e32 v83, 0xffff0000, v83
	v_fma_f32 v139, -v125, v138, 1.0
	v_fmac_f32_e32 v138, v139, v138
	v_div_scale_f32 v139, vcc, 1.0, v98, 1.0
	v_mul_f32_e32 v140, v139, v138
	v_fma_f32 v141, -v125, v140, v139
	v_fmac_f32_e32 v140, v141, v138
	v_fma_f32 v125, -v125, v140, v139
	v_div_fmas_f32 v125, v125, v138, v140
	v_div_fixup_f32 v98, v125, v98, 1.0
	v_mov_b32_e32 v138, v126
	v_mov_b32_e32 v139, v92
	v_mov_b32_e32 v92, v127
	v_pk_mul_f32 v[138:139], v[98:99], v[138:139] op_sel_hi:[0,1]
	v_pk_mul_f32 v[92:93], v[98:99], v[92:93] op_sel_hi:[0,1]
	v_pk_mul_f32 v[88:89], v[98:99], v[88:89] op_sel_hi:[0,1]
	v_mov_b32_e32 v125, v121
	v_pk_fma_f32 v[84:85], v[62:63], v[92:93], v[84:85]
	v_pk_fma_f32 v[92:93], v[60:61], v[138:139], v[128:129]
	v_mov_b32_e32 v126, v130
	v_mov_b32_e32 v127, v94
	v_mov_b32_e32 v94, v131
	v_pk_fma_f32 v[88:89], v[38:39], v[88:89], v[80:81]
	v_pk_mul_f32 v[80:81], v[98:99], v[124:125] op_sel_hi:[0,1]
	v_pk_mul_f32 v[90:91], v[98:99], v[90:91] op_sel_hi:[0,1]
	v_pk_mul_f32 v[126:127], v[98:99], v[126:127] op_sel_hi:[0,1]
	v_pk_mul_f32 v[94:95], v[98:99], v[94:95] op_sel_hi:[0,1]
	v_pk_fma_f32 v[90:91], v[58:59], v[90:91], v[82:83]
	v_pk_fma_f32 v[124:125], v[56:57], v[80:81], v[136:137]
	v_pk_mul_f32 v[80:81], v[84:85], v[84:85]
	v_pk_mul_f32 v[82:83], v[92:93], v[92:93]
	v_pk_fma_f32 v[86:87], v[30:31], v[94:95], v[86:87]
	v_pk_fma_f32 v[94:95], v[28:29], v[126:127], v[132:133]
	v_pk_mov_b32 v[126:127], v[82:83], v[80:81] op_sel:[1,0]
	v_mov_b32_e32 v83, v81
	v_pk_mul_f32 v[122:123], v[98:99], v[122:123] op_sel_hi:[0,1]
	v_pk_add_f32 v[80:81], v[126:127], v[82:83]
	v_pk_fma_f32 v[122:123], v[36:37], v[122:123], v[134:135]
	v_pk_add_f32 v[80:81], v[80:81], v[80:81] op_sel_hi:[0,1]
	v_pk_mul_f32 v[82:83], v[86:87], v[86:87]
	v_pk_mul_f32 v[126:127], v[94:95], v[94:95]
	v_mul_f32_e32 v80, v122, v122
	v_pk_mov_b32 v[128:129], v[126:127], v[82:83] op_sel:[1,0]
	v_mov_b32_e32 v127, v83
	v_pk_add_f32 v[82:83], v[128:129], v[126:127]
	v_pk_fma_f32 v[126:127], v[122:123], v[122:123], v[80:81] op_sel_hi:[1,1,0]
	v_mul_f32_e32 v80, v88, v88
	v_pk_add_f32 v[82:83], v[82:83], v[82:83] op_sel_hi:[0,1]
	v_pk_fma_f32 v[128:129], v[88:89], v[88:89], v[80:81] op_sel_hi:[1,1,0]
	v_mul_f32_e32 v126, v124, v124
	v_mul_f32_e32 v128, v125, v125
	v_mul_f32_e32 v80, v90, v90
	v_mul_f32_e32 v82, v91, v91
	v_pk_add_f32 v[126:127], v[126:127], v[128:129]
	v_pk_add_f32 v[80:81], v[80:81], v[82:83]
	v_cvt_pk_bf16_f32 v82, v94, v95
	v_pk_add_f32 v[80:81], v[126:127], v[80:81]
	v_lshl_add_u64 v[126:127], s[10:11], 0, v[96:97]
	v_add_f32_e32 v80, v80, v81
	ds_bpermute_b32 v81, v109, v80
	v_add_co_u32_e32 v126, vcc, s36, v126
	v_cvt_pk_bf16_f32 v83, v86, v87
	s_nop 0
	v_addc_co_u32_e32 v127, vcc, 0, v127, vcc
	s_waitcnt lgkmcnt(0)
	v_add_f32_e32 v80, v80, v81
	ds_bpermute_b32 v81, v114, v80
	s_waitcnt lgkmcnt(0)
	v_add_f32_e32 v80, v80, v81
	ds_bpermute_b32 v81, v115, v80
	s_waitcnt lgkmcnt(0)
	v_add_f32_e32 v80, v80, v81
	ds_bpermute_b32 v81, v116, v80
	s_waitcnt lgkmcnt(0)
	v_add_f32_e32 v98, v80, v81
	ds_bpermute_b32 v121, v117, v98
	v_cvt_pk_bf16_f32 v80, v92, v93
	v_cvt_pk_bf16_f32 v81, v84, v85
	global_store_dwordx4 v[126:127], v[80:83], off nt
	s_waitcnt lgkmcnt(0)
	v_add_f32_e32 v98, v98, v121
	ds_bpermute_b32 v121, v118, v98
	v_cvt_pk_bf16_f32 v80, v122, v123
	v_cvt_pk_bf16_f32 v81, v88, v89
	s_waitcnt lgkmcnt(0)
	v_add_f32_e32 v98, v98, v121
	v_fmamk_f32 v98, v98, 0x3a800000, v119
	v_mul_f32_e32 v121, 0x4f800000, v98
	v_cmp_gt_f32_e32 vcc, s27, v98
	s_nop 1
	v_cndmask_b32_e32 v98, v98, v121, vcc
	v_sqrt_f32_e32 v121, v98
	s_nop 0
	v_add_u32_e32 v82, -1, v121
	v_fma_f32 v83, -v82, v121, v98
	v_cmp_ge_f32_e64 s[2:3], 0, v83
	v_add_u32_e32 v83, 1, v121
	s_nop 0
	v_cndmask_b32_e64 v82, v121, v82, s[2:3]
	v_fma_f32 v121, -v83, v121, v98
	v_cmp_lt_f32_e64 s[2:3], 0, v121
	s_nop 1
	v_cndmask_b32_e64 v82, v82, v83, s[2:3]
	v_mul_f32_e32 v83, 0x37800000, v82
	v_cndmask_b32_e32 v82, v82, v83, vcc
	v_cmp_class_f32_e32 vcc, v98, v120
	v_cvt_pk_bf16_f32 v83, v90, v91
	s_nop 0
	v_cndmask_b32_e32 v98, v82, v98, vcc
	v_div_scale_f32 v121, s[2:3], v98, v98, 1.0
	v_rcp_f32_e32 v128, v121
	v_cvt_pk_bf16_f32 v82, v124, v125
	global_store_dwordx4 v[126:127], v[80:83], off offset:1024 nt
	v_lshl_add_u64 v[126:127], s[8:9], 0, v[96:97]
	s_nop 0
	v_fma_f32 v80, -v121, v128, 1.0
	v_fmac_f32_e32 v128, v80, v128
	v_div_scale_f32 v80, vcc, 1.0, v98, 1.0
	v_mul_f32_e32 v81, v80, v128
	v_fma_f32 v82, -v121, v81, v80
	v_fmac_f32_e32 v81, v82, v128
	v_fma_f32 v80, -v121, v81, v80
	v_div_fmas_f32 v80, v80, v128, v81
	v_div_fixup_f32 v98, v80, v98, 1.0
	v_pk_mul_f32 v[80:81], v[92:93], v[98:99] op_sel_hi:[1,0]
	v_pk_mul_f32 v[82:83], v[84:85], v[98:99] op_sel_hi:[1,0]
	v_pk_mul_f32 v[84:85], v[94:95], v[98:99] op_sel_hi:[1,0]
	v_pk_fma_f32 v[82:83], v[66:67], v[82:83], v[34:35]
	v_pk_fma_f32 v[80:81], v[64:65], v[80:81], v[32:33]
	v_pk_mul_f32 v[86:87], v[86:87], v[98:99] op_sel_hi:[1,0]
	v_pk_fma_f32 v[84:85], v[68:69], v[84:85], v[20:21]
	v_pk_fma_f32 v[86:87], v[70:71], v[86:87], v[22:23]
	v_cvt_pk_bf16_f32 v80, v80, v81
	v_cvt_pk_bf16_f32 v81, v82, v83
	v_cvt_pk_bf16_f32 v82, v84, v85
	v_add_co_u32_e32 v84, vcc, s37, v126
	v_cvt_pk_bf16_f32 v83, v86, v87
	s_nop 0
	v_addc_co_u32_e32 v85, vcc, 0, v127, vcc
	global_store_dwordx4 v[84:85], v[80:83], off
	v_pk_mul_f32 v[86:87], v[124:125], v[98:99] op_sel_hi:[1,0]
	s_nop 0
	v_pk_mul_f32 v[80:81], v[122:123], v[98:99] op_sel_hi:[1,0]
	v_pk_mul_f32 v[82:83], v[88:89], v[98:99] op_sel_hi:[1,0]
	v_pk_mul_f32 v[88:89], v[90:91], v[98:99] op_sel_hi:[1,0]
	v_pk_fma_f32 v[82:83], v[74:75], v[82:83], v[26:27]
	v_pk_fma_f32 v[80:81], v[72:73], v[80:81], v[24:25]
	v_pk_fma_f32 v[88:89], v[78:79], v[88:89], v[18:19]
	v_pk_fma_f32 v[86:87], v[76:77], v[86:87], v[16:17]
	v_cvt_pk_bf16_f32 v80, v80, v81
	v_cvt_pk_bf16_f32 v81, v82, v83
	v_cvt_pk_bf16_f32 v82, v86, v87
	v_cvt_pk_bf16_f32 v83, v88, v89
	global_store_dwordx4 v[84:85], v[80:83], off offset:1024
	s_cbranch_scc1 .LBB0_1186
	s_ashr_i32 s2, s22, 13
	s_cmp_eq_u32 s2, s39
	s_cbranch_scc1 .LBB0_1194
	s_mul_i32 s7, s2, 0x6000
	s_mul_hi_i32 s3, s2, 0x6000
	s_add_u32 s34, s52, s7
	s_addc_u32 s35, s53, s3
	v_lshlrev_b32_e32 v98, 4, v108
	v_lshl_add_u64 v[16:17], s[34:35], 0, v[98:99]
	v_add_co_u32_e32 v22, vcc, s24, v16
	v_lshl_add_u64 v[18:19], v[16:17], 0, s[16:17]
	s_nop 0
	v_addc_co_u32_e32 v23, vcc, 0, v17, vcc
	v_add_co_u32_e32 v32, vcc, s25, v16
	v_lshl_add_u64 v[20:21], v[16:17], 0, s[18:19]
	s_nop 0
	v_addc_co_u32_e32 v33, vcc, 0, v17, vcc
	v_lshl_add_u64 v[24:25], v[16:17], 0, s[20:21]
	global_load_dwordx4 v[28:31], v[110:111], off offset:16
	global_load_dwordx4 v[60:63], v[110:111], off
	global_load_dwordx4 v[36:39], v[22:23], off
	global_load_dwordx4 v[56:59], v[18:19], off offset:16
	global_load_dwordx4 v[64:67], v[20:21], off offset:16
	global_load_dwordx4 v[68:71], v[110:111], off offset:2064
	global_load_dwordx4 v[72:75], v[110:111], off offset:2048
	global_load_dwordx4 v[76:79], v[18:19], off offset:2048
	global_load_dwordx4 v[80:83], v[20:21], off offset:2064
	global_load_dwordx4 v[84:87], v[20:21], off offset:2048
	global_load_dwordx4 v[88:91], v[18:19], off offset:2064
	global_load_dwordx4 v[92:95], v[32:33], off offset:-4096
	global_load_dwordx4 v[122:125], v[112:113], off
	global_load_dwordx4 v[126:129], v[112:113], off offset:16
	global_load_dwordx4 v[130:133], v[112:113], off offset:2064
	global_load_dwordx4 v[134:137], v[112:113], off offset:2048
	global_load_dwordx4 v[16:19], v[24:25], off offset:2064
	global_load_dwordx4 v[20:23], v[24:25], off offset:16
	s_nop 0
	global_load_dwordx4 v[24:27], v[24:25], off offset:2048
	s_nop 0
	global_load_dwordx4 v[32:35], v[32:33], off
	s_mov_b32 s39, s2
	s_waitcnt vmcnt(17)
	v_pk_add_f32 v[138:139], v[38:39], 1.0 op_sel_hi:[1,0]
	v_pk_add_f32 v[140:141], v[36:37], 1.0 op_sel_hi:[1,0]
	s_waitcnt vmcnt(15)
	v_pk_add_f32 v[142:143], v[66:67], 1.0 op_sel_hi:[1,0]
	v_pk_add_f32 v[144:145], v[64:65], 1.0 op_sel_hi:[1,0]
	s_waitcnt vmcnt(12)
	v_pk_mul_f32 v[38:39], v[74:75], v[78:79]
	v_pk_mul_f32 v[36:37], v[72:73], v[76:77]
	s_waitcnt vmcnt(10)
	v_pk_add_f32 v[72:73], v[86:87], 1.0 op_sel_hi:[1,0]
	v_pk_add_f32 v[76:77], v[84:85], 1.0 op_sel_hi:[1,0]
	v_pk_add_f32 v[78:79], v[82:83], 1.0 op_sel_hi:[1,0]
	v_pk_add_f32 v[80:81], v[80:81], 1.0 op_sel_hi:[1,0]
	v_pk_mul_f32 v[30:31], v[30:31], v[58:59]
	v_pk_mul_f32 v[28:29], v[28:29], v[56:57]
	s_waitcnt vmcnt(9)
	v_pk_mul_f32 v[58:59], v[70:71], v[90:91]
	v_pk_mul_f32 v[56:57], v[68:69], v[88:89]
	s_waitcnt vmcnt(8)
	v_pk_mul_f32 v[62:63], v[62:63], v[94:95]
	v_pk_mul_f32 v[60:61], v[60:61], v[92:93]
	s_waitcnt vmcnt(7)
	v_pk_mul_f32 v[66:67], v[124:125], v[138:139]
	v_pk_mul_f32 v[64:65], v[122:123], v[140:141]
	s_waitcnt vmcnt(6)
	v_pk_mul_f32 v[70:71], v[128:129], v[142:143]
	v_pk_mul_f32 v[68:69], v[126:127], v[144:145]
	s_waitcnt vmcnt(4)
	v_pk_mul_f32 v[74:75], v[136:137], v[72:73]
	v_pk_mul_f32 v[72:73], v[134:135], v[76:77]
	v_pk_mul_f32 v[78:79], v[132:133], v[78:79]
	v_pk_mul_f32 v[76:77], v[130:131], v[80:81]

.LBB0_2024:
	v_lshlrev_b32_e32 v127, 16, v93
	v_lshlrev_b32_e32 v126, 16, v92
	v_and_b32_e32 v93, 0xffff0000, v93
	v_and_b32_e32 v92, 0xffff0000, v92
	v_lshlrev_b32_e32 v131, 16, v95
	v_lshlrev_b32_e32 v130, 16, v94
	v_and_b32_e32 v95, 0xffff0000, v95
	v_and_b32_e32 v94, 0xffff0000, v94
	v_lshlrev_b32_e32 v122, 16, v88
	v_and_b32_e32 v123, 0xffff0000, v88
	v_lshlrev_b32_e32 v124, 16, v90
	v_pk_mul_f32 v[128:129], v[92:93], v[92:93]
	v_pk_mul_f32 v[132:133], v[94:95], v[94:95]
	v_lshlrev_b32_e32 v88, 16, v89
	v_pk_fma_f32 v[128:129], v[126:127], v[126:127], v[128:129]
	v_pk_fma_f32 v[132:133], v[130:131], v[130:131], v[132:133]
	v_mul_f32_e32 v125, v122, v122
	v_mul_f32_e32 v135, v123, v123
	v_and_b32_e32 v89, 0xffff0000, v89
	v_mul_f32_e32 v98, v88, v88
	v_mov_b32_e32 v134, v124
	v_and_b32_e32 v121, 0xffff0000, v90
	v_lshlrev_b32_e32 v90, 16, v91
	v_and_b32_e32 v91, 0xffff0000, v91
	v_pk_add_f32 v[128:129], v[128:129], v[128:129] op_sel_hi:[0,1]
	v_pk_add_f32 v[132:133], v[132:133], v[132:133] op_sel_hi:[0,1]
	v_pk_fma_f32 v[136:137], v[88:89], v[88:89], v[98:99] op_sel_hi:[1,1,0]
	v_pk_add_f32 v[134:135], v[124:125], v[134:135]
	v_mul_f32_e32 v136, v121, v121
	v_mul_f32_e32 v128, v90, v90
	v_mul_f32_e32 v132, v91, v91
	v_mul_f32_e32 v138, v124, v124
	v_mov_b32_e32 v139, v135
	v_pk_add_f32 v[134:135], v[138:139], v[136:137]
	v_pk_add_f32 v[128:129], v[128:129], v[132:133]
	v_lshlrev_b32_e32 v136, 16, v82
	v_pk_add_f32 v[128:129], v[134:135], v[128:129]
	v_lshlrev_b32_e32 v134, 16, v80
	v_add_f32_e32 v98, v128, v129
	ds_bpermute_b32 v125, v109, v98
	v_and_b32_e32 v135, 0xffff0000, v80
	v_lshlrev_b32_e32 v128, 16, v84
	v_and_b32_e32 v129, 0xffff0000, v84
	v_lshlrev_b32_e32 v84, 16, v85
	s_waitcnt lgkmcnt(0)
	v_add_f32_e32 v98, v98, v125
	ds_bpermute_b32 v125, v114, v98
	v_and_b32_e32 v85, 0xffff0000, v85
	v_lshlrev_b32_e32 v132, 16, v86
	v_and_b32_e32 v133, 0xffff0000, v86
	v_lshlrev_b32_e32 v86, 16, v87
	s_waitcnt lgkmcnt(0)
	v_add_f32_e32 v98, v98, v125
	ds_bpermute_b32 v125, v115, v98
	v_and_b32_e32 v87, 0xffff0000, v87
	s_add_i32 s22, s6, -2
	s_cmp_ge_i32 s22, s26
	s_waitcnt lgkmcnt(0)
	v_add_f32_e32 v98, v98, v125
	ds_bpermute_b32 v125, v116, v98
	s_waitcnt lgkmcnt(0)
	v_add_f32_e32 v98, v98, v125
	ds_bpermute_b32 v125, v117, v98
	s_waitcnt lgkmcnt(0)
	v_add_f32_e32 v98, v98, v125
	ds_bpermute_b32 v125, v118, v98
	s_waitcnt lgkmcnt(0)
	v_add_f32_e32 v80, v98, v125
	v_fmamk_f32 v80, v80, 0x3a800000, v119
	v_mul_f32_e32 v98, 0x4f800000, v80
	v_cmp_gt_f32_e32 vcc, s27, v80
	s_nop 1
	v_cndmask_b32_e32 v98, v80, v98, vcc
	v_sqrt_f32_e32 v125, v98
	v_lshlrev_b32_e32 v80, 16, v81
	v_and_b32_e32 v81, 0xffff0000, v81
	v_add_u32_e32 v137, -1, v125
	v_fma_f32 v138, -v137, v125, v98
	v_cmp_ge_f32_e64 s[2:3], 0, v138
	v_add_u32_e32 v138, 1, v125
	s_nop 0
	v_cndmask_b32_e64 v137, v125, v137, s[2:3]
	v_fma_f32 v125, -v138, v125, v98
	v_cmp_lt_f32_e64 s[2:3], 0, v125
	s_nop 1
	v_cndmask_b32_e64 v125, v137, v138, s[2:3]
	v_mul_f32_e32 v137, 0x37800000, v125
	v_cndmask_b32_e32 v125, v125, v137, vcc
	v_cmp_class_f32_e32 vcc, v98, v120
	v_and_b32_e32 v137, 0xffff0000, v82
	v_lshlrev_b32_e32 v82, 16, v83
	v_cndmask_b32_e32 v98, v125, v98, vcc
	v_div_scale_f32 v125, s[2:3], v98, v98, 1.0
	v_rcp_f32_e32 v138, v125
	v_and_b32_e32 v83, 0xffff0000, v83
	v_fma_f32 v139, -v125, v138, 1.0
	v_fmac_f32_e32 v138, v139, v138
	v_div_scale_f32 v139, vcc, 1.0, v98, 1.0
	v_mul_f32_e32 v140, v139, v138
	v_fma_f32 v141, -v125, v140, v139
	v_fmac_f32_e32 v140, v141, v138
	v_fma_f32 v125, -v125, v140, v139
	v_div_fmas_f32 v125, v125, v138, v140
	v_div_fixup_f32 v98, v125, v98, 1.0
	v_mov_b32_e32 v138, v126
	v_mov_b32_e32 v139, v92
	v_mov_b32_e32 v92, v127
	v_pk_mul_f32 v[138:139], v[98:99], v[138:139] op_sel_hi:[0,1]
	v_pk_mul_f32 v[92:93], v[98:99], v[92:93] op_sel_hi:[0,1]
	v_pk_mul_f32 v[88:89], v[98:99], v[88:89] op_sel_hi:[0,1]
	v_mov_b32_e32 v125, v121
	v_pk_fma_f32 v[84:85], v[62:63], v[92:93], v[84:85]
	v_pk_fma_f32 v[92:93], v[60:61], v[138:139], v[128:129]
	v_mov_b32_e32 v126, v130
	v_mov_b32_e32 v127, v94
	v_mov_b32_e32 v94, v131
	v_pk_fma_f32 v[88:89], v[38:39], v[88:89], v[80:81]
	v_pk_mul_f32 v[80:81], v[98:99], v[124:125] op_sel_hi:[0,1]
	v_pk_mul_f32 v[90:91], v[98:99], v[90:91] op_sel_hi:[0,1]
	v_pk_mul_f32 v[126:127], v[98:99], v[126:127] op_sel_hi:[0,1]
	v_pk_mul_f32 v[94:95], v[98:99], v[94:95] op_sel_hi:[0,1]
	v_pk_fma_f32 v[90:91], v[58:59], v[90:91], v[82:83]
	v_pk_fma_f32 v[124:125], v[56:57], v[80:81], v[136:137]
	v_pk_mul_f32 v[80:81], v[84:85], v[84:85]
	v_pk_mul_f32 v[82:83], v[92:93], v[92:93]
	v_pk_fma_f32 v[86:87], v[30:31], v[94:95], v[86:87]
	v_pk_fma_f32 v[94:95], v[28:29], v[126:127], v[132:133]
	v_pk_mov_b32 v[126:127], v[82:83], v[80:81] op_sel:[1,0]
	v_mov_b32_e32 v83, v81
	v_pk_mul_f32 v[122:123], v[98:99], v[122:123] op_sel_hi:[0,1]
	v_pk_add_f32 v[80:81], v[126:127], v[82:83]
	v_pk_fma_f32 v[122:123], v[36:37], v[122:123], v[134:135]
	v_pk_add_f32 v[80:81], v[80:81], v[80:81] op_sel_hi:[0,1]
	v_pk_mul_f32 v[82:83], v[86:87], v[86:87]
	v_pk_mul_f32 v[126:127], v[94:95], v[94:95]
	v_mul_f32_e32 v80, v122, v122
	v_pk_mov_b32 v[128:129], v[126:127], v[82:83] op_sel:[1,0]
	v_mov_b32_e32 v127, v83
	v_pk_add_f32 v[82:83], v[128:129], v[126:127]
	v_pk_fma_f32 v[126:127], v[122:123], v[122:123], v[80:81] op_sel_hi:[1,1,0]
	v_mul_f32_e32 v80, v88, v88
	v_pk_add_f32 v[82:83], v[82:83], v[82:83] op_sel_hi:[0,1]
	v_pk_fma_f32 v[128:129], v[88:89], v[88:89], v[80:81] op_sel_hi:[1,1,0]
	v_mul_f32_e32 v126, v124, v124
	v_mul_f32_e32 v128, v125, v125
	v_mul_f32_e32 v80, v90, v90
	v_mul_f32_e32 v82, v91, v91
	v_pk_add_f32 v[126:127], v[126:127], v[128:129]
	v_pk_add_f32 v[80:81], v[80:81], v[82:83]
	v_cvt_pk_bf16_f32 v82, v94, v95
	v_pk_add_f32 v[80:81], v[126:127], v[80:81]
	v_lshl_add_u64 v[126:127], s[10:11], 0, v[96:97]
	v_add_f32_e32 v80, v80, v81
	ds_bpermute_b32 v81, v109, v80
	v_add_co_u32_e32 v126, vcc, s36, v126
	v_cvt_pk_bf16_f32 v83, v86, v87
	s_nop 0
	v_addc_co_u32_e32 v127, vcc, 0, v127, vcc
	s_waitcnt lgkmcnt(0)
	v_add_f32_e32 v80, v80, v81
	ds_bpermute_b32 v81, v114, v80
	s_waitcnt lgkmcnt(0)
	v_add_f32_e32 v80, v80, v81
	ds_bpermute_b32 v81, v115, v80
	s_waitcnt lgkmcnt(0)
	v_add_f32_e32 v80, v80, v81
	ds_bpermute_b32 v81, v116, v80
	s_waitcnt lgkmcnt(0)
	v_add_f32_e32 v98, v80, v81
	ds_bpermute_b32 v121, v117, v98
	v_cvt_pk_bf16_f32 v80, v92, v93
	v_cvt_pk_bf16_f32 v81, v84, v85
	global_store_dwordx4 v[126:127], v[80:83], off nt
	s_waitcnt lgkmcnt(0)
	v_add_f32_e32 v98, v98, v121
	ds_bpermute_b32 v121, v118, v98
	v_cvt_pk_bf16_f32 v80, v122, v123
	v_cvt_pk_bf16_f32 v81, v88, v89
	s_waitcnt lgkmcnt(0)
	v_add_f32_e32 v98, v98, v121
	v_fmamk_f32 v98, v98, 0x3a800000, v119
	v_mul_f32_e32 v121, 0x4f800000, v98
	v_cmp_gt_f32_e32 vcc, s27, v98
	s_nop 1
	v_cndmask_b32_e32 v98, v98, v121, vcc
	v_sqrt_f32_e32 v121, v98
	s_nop 0
	v_add_u32_e32 v82, -1, v121
	v_fma_f32 v83, -v82, v121, v98
	v_cmp_ge_f32_e64 s[2:3], 0, v83
	v_add_u32_e32 v83, 1, v121
	s_nop 0
	v_cndmask_b32_e64 v82, v121, v82, s[2:3]
	v_fma_f32 v121, -v83, v121, v98
	v_cmp_lt_f32_e64 s[2:3], 0, v121
	s_nop 1
	v_cndmask_b32_e64 v82, v82, v83, s[2:3]
	v_mul_f32_e32 v83, 0x37800000, v82
	v_cndmask_b32_e32 v82, v82, v83, vcc
	v_cmp_class_f32_e32 vcc, v98, v120
	v_cvt_pk_bf16_f32 v83, v90, v91
	s_nop 0
	v_cndmask_b32_e32 v98, v82, v98, vcc
	v_div_scale_f32 v121, s[2:3], v98, v98, 1.0
	v_rcp_f32_e32 v128, v121
	v_cvt_pk_bf16_f32 v82, v124, v125
	global_store_dwordx4 v[126:127], v[80:83], off offset:1024 nt
	v_lshl_add_u64 v[126:127], s[8:9], 0, v[96:97]
	s_nop 0
	v_fma_f32 v80, -v121, v128, 1.0
	v_fmac_f32_e32 v128, v80, v128
	v_div_scale_f32 v80, vcc, 1.0, v98, 1.0
	v_mul_f32_e32 v81, v80, v128
	v_fma_f32 v82, -v121, v81, v80
	v_fmac_f32_e32 v81, v82, v128
	v_fma_f32 v80, -v121, v81, v80
	v_div_fmas_f32 v80, v80, v128, v81
	v_div_fixup_f32 v98, v80, v98, 1.0
	v_pk_mul_f32 v[80:81], v[92:93], v[98:99] op_sel_hi:[1,0]
	v_pk_mul_f32 v[82:83], v[84:85], v[98:99] op_sel_hi:[1,0]
	v_pk_mul_f32 v[84:85], v[94:95], v[98:99] op_sel_hi:[1,0]
	v_pk_fma_f32 v[82:83], v[66:67], v[82:83], v[34:35]
	v_pk_fma_f32 v[80:81], v[64:65], v[80:81], v[32:33]
	v_pk_mul_f32 v[86:87], v[86:87], v[98:99] op_sel_hi:[1,0]
	v_pk_fma_f32 v[84:85], v[68:69], v[84:85], v[20:21]
	v_pk_fma_f32 v[86:87], v[70:71], v[86:87], v[22:23]
	v_cvt_pk_bf16_f32 v80, v80, v81
	v_cvt_pk_bf16_f32 v81, v82, v83
	v_cvt_pk_bf16_f32 v82, v84, v85
	v_add_co_u32_e32 v84, vcc, s37, v126
	v_cvt_pk_bf16_f32 v83, v86, v87
	s_nop 0
	v_addc_co_u32_e32 v85, vcc, 0, v127, vcc
	global_store_dwordx4 v[84:85], v[80:83], off
	v_pk_mul_f32 v[86:87], v[124:125], v[98:99] op_sel_hi:[1,0]
	s_nop 0
	v_pk_mul_f32 v[80:81], v[122:123], v[98:99] op_sel_hi:[1,0]
	v_pk_mul_f32 v[82:83], v[88:89], v[98:99] op_sel_hi:[1,0]
	v_pk_mul_f32 v[88:89], v[90:91], v[98:99] op_sel_hi:[1,0]
	v_pk_fma_f32 v[82:83], v[74:75], v[82:83], v[26:27]
	v_pk_fma_f32 v[80:81], v[72:73], v[80:81], v[24:25]
	v_pk_fma_f32 v[88:89], v[78:79], v[88:89], v[18:19]
	v_pk_fma_f32 v[86:87], v[76:77], v[86:87], v[16:17]
	v_cvt_pk_bf16_f32 v80, v80, v81
	v_cvt_pk_bf16_f32 v81, v82, v83
	v_cvt_pk_bf16_f32 v82, v86, v87
	v_cvt_pk_bf16_f32 v83, v88, v89
	global_store_dwordx4 v[84:85], v[80:83], off offset:1024
	s_cbranch_scc1 .LBB0_2019
	s_ashr_i32 s2, s22, 13
	s_cmp_eq_u32 s2, s39
	s_cbranch_scc1 .LBB0_2027
	s_mul_i32 s7, s2, 0x6000
	s_mul_hi_i32 s3, s2, 0x6000
	s_add_u32 s34, s46, s7
	s_addc_u32 s35, s47, s3
	v_lshlrev_b32_e32 v98, 4, v108
	v_lshl_add_u64 v[16:17], s[34:35], 0, v[98:99]
	v_add_co_u32_e32 v22, vcc, s24, v16
	v_lshl_add_u64 v[18:19], v[16:17], 0, s[16:17]
	s_nop 0
	v_addc_co_u32_e32 v23, vcc, 0, v17, vcc
	v_add_co_u32_e32 v32, vcc, s25, v16
	v_lshl_add_u64 v[20:21], v[16:17], 0, s[18:19]
	s_nop 0
	v_addc_co_u32_e32 v33, vcc, 0, v17, vcc
	v_lshl_add_u64 v[24:25], v[16:17], 0, s[20:21]
	global_load_dwordx4 v[28:31], v[110:111], off offset:16
	global_load_dwordx4 v[60:63], v[110:111], off
	global_load_dwordx4 v[36:39], v[22:23], off
	global_load_dwordx4 v[56:59], v[18:19], off offset:16
	global_load_dwordx4 v[64:67], v[20:21], off offset:16
	global_load_dwordx4 v[68:71], v[110:111], off offset:2064
	global_load_dwordx4 v[72:75], v[110:111], off offset:2048
	global_load_dwordx4 v[76:79], v[18:19], off offset:2048
	global_load_dwordx4 v[80:83], v[20:21], off offset:2064
	global_load_dwordx4 v[84:87], v[20:21], off offset:2048
	global_load_dwordx4 v[88:91], v[18:19], off offset:2064
	global_load_dwordx4 v[92:95], v[32:33], off offset:-4096
	global_load_dwordx4 v[122:125], v[112:113], off
	global_load_dwordx4 v[126:129], v[112:113], off offset:16
	global_load_dwordx4 v[130:133], v[112:113], off offset:2064
	global_load_dwordx4 v[134:137], v[112:113], off offset:2048
	global_load_dwordx4 v[16:19], v[24:25], off offset:2064
	global_load_dwordx4 v[20:23], v[24:25], off offset:16
	s_nop 0
	global_load_dwordx4 v[24:27], v[24:25], off offset:2048
	s_nop 0
	global_load_dwordx4 v[32:35], v[32:33], off
	s_mov_b32 s39, s2
	s_waitcnt vmcnt(17)
	v_pk_add_f32 v[138:139], v[38:39], 1.0 op_sel_hi:[1,0]
	v_pk_add_f32 v[140:141], v[36:37], 1.0 op_sel_hi:[1,0]
	s_waitcnt vmcnt(15)
	v_pk_add_f32 v[142:143], v[66:67], 1.0 op_sel_hi:[1,0]
	v_pk_add_f32 v[144:145], v[64:65], 1.0 op_sel_hi:[1,0]
	s_waitcnt vmcnt(12)
	v_pk_mul_f32 v[38:39], v[74:75], v[78:79]
	v_pk_mul_f32 v[36:37], v[72:73], v[76:77]
	s_waitcnt vmcnt(10)
	v_pk_add_f32 v[72:73], v[86:87], 1.0 op_sel_hi:[1,0]
	v_pk_add_f32 v[76:77], v[84:85], 1.0 op_sel_hi:[1,0]
	v_pk_add_f32 v[78:79], v[82:83], 1.0 op_sel_hi:[1,0]
	v_pk_add_f32 v[80:81], v[80:81], 1.0 op_sel_hi:[1,0]
	v_pk_mul_f32 v[30:31], v[30:31], v[58:59]
	v_pk_mul_f32 v[28:29], v[28:29], v[56:57]
	s_waitcnt vmcnt(9)
	v_pk_mul_f32 v[58:59], v[70:71], v[90:91]
	v_pk_mul_f32 v[56:57], v[68:69], v[88:89]
	s_waitcnt vmcnt(8)
	v_pk_mul_f32 v[62:63], v[62:63], v[94:95]
	v_pk_mul_f32 v[60:61], v[60:61], v[92:93]
	s_waitcnt vmcnt(7)
	v_pk_mul_f32 v[66:67], v[124:125], v[138:139]
	v_pk_mul_f32 v[64:65], v[122:123], v[140:141]
	s_waitcnt vmcnt(6)
	v_pk_mul_f32 v[70:71], v[128:129], v[142:143]
	v_pk_mul_f32 v[68:69], v[126:127], v[144:145]
	s_waitcnt vmcnt(4)
	v_pk_mul_f32 v[74:75], v[136:137], v[72:73]
	v_pk_mul_f32 v[72:73], v[134:135], v[76:77]
	v_pk_mul_f32 v[78:79], v[132:133], v[78:79]
	v_pk_mul_f32 v[76:77], v[130:131], v[80:81]
